# units after the first in multi-unit GEMM phases (gate/up, QKV, q_b/kv_b): the 128 v_mov accumulator zeroing is skipped and the first MFMA of each accumulator in the peeled first K iteration takes C=0;
# speedup vs baseline: 1.0142x; 1.0090x over previous
.LBB0_429:
	s_ashr_i32 s27, s26, 31
	s_lshl_b64 s[28:29], s[26:27], 18
	s_cmp_eq_u32 s44, 0
	s_cselect_b32 s9, s79, s83
	s_cselect_b32 s7, s80, s84
	s_cselect_b32 s21, s81, s77
	s_cselect_b32 s27, s82, s85
	s_add_u32 s28, s9, s28
	s_addc_u32 s29, s7, s29
	s_and_b64 s[30:31], s[22:23], exec
	s_cselect_b32 s7, s29, s37
	s_cselect_b32 s9, s28, s36
	s_ashr_i32 s25, s24, 31
	s_lshl_b64 s[30:31], s[24:25], 18
	s_add_u32 s30, s21, s30
	s_addc_u32 s31, s27, s31
	s_and_b64 s[38:39], s[22:23], exec
	s_cselect_b32 s21, s31, s35
	s_cselect_b32 s25, s30, s34
	s_add_u32 s27, s34, 0x100
	s_addc_u32 s45, s35, 0
	s_add_u32 s34, s36, 0x20080
	s_addc_u32 s35, s37, 0
	s_mov_b32 s48, -2
	s_cmp_eq_u32 s99, 0
	s_cbranch_scc0 .Lpeel_G67
	v_mov_b32_e32 v2, 0
	v_mov_b32_e32 v3, v2
	v_mov_b32_e32 v4, v2
	v_mov_b32_e32 v5, v2
	v_mov_b32_e32 v6, v2
	v_mov_b32_e32 v7, v2
	v_mov_b32_e32 v8, v2
	v_mov_b32_e32 v9, v2
	v_mov_b32_e32 v18, v2
	v_mov_b32_e32 v19, v2
	v_mov_b32_e32 v20, v2
	v_mov_b32_e32 v21, v2
	v_mov_b32_e32 v22, v2
	v_mov_b32_e32 v23, v2
	v_mov_b32_e32 v24, v2
	v_mov_b32_e32 v25, v2
	v_mov_b32_e32 v34, v2
	v_mov_b32_e32 v35, v2
	v_mov_b32_e32 v36, v2
	v_mov_b32_e32 v37, v2
	v_mov_b32_e32 v38, v2
	v_mov_b32_e32 v39, v2
	v_mov_b32_e32 v40, v2
	v_mov_b32_e32 v41, v2
	v_mov_b32_e32 v50, v2
	v_mov_b32_e32 v51, v2
	v_mov_b32_e32 v52, v2
	v_mov_b32_e32 v53, v2
	v_mov_b32_e32 v54, v2
	v_mov_b32_e32 v55, v2
	v_mov_b32_e32 v56, v2
	v_mov_b32_e32 v57, v2
	v_mov_b32_e32 v10, v2
	v_mov_b32_e32 v11, v2
	v_mov_b32_e32 v12, v2
	v_mov_b32_e32 v13, v2
	v_mov_b32_e32 v14, v2
	v_mov_b32_e32 v15, v2
	v_mov_b32_e32 v16, v2
	v_mov_b32_e32 v17, v2
	v_mov_b32_e32 v26, v2
	v_mov_b32_e32 v27, v2
	v_mov_b32_e32 v28, v2
	v_mov_b32_e32 v29, v2
	v_mov_b32_e32 v30, v2
	v_mov_b32_e32 v31, v2
	v_mov_b32_e32 v32, v2
	v_mov_b32_e32 v33, v2
	v_mov_b32_e32 v42, v2
	v_mov_b32_e32 v43, v2
	v_mov_b32_e32 v44, v2
	v_mov_b32_e32 v45, v2
	v_mov_b32_e32 v46, v2
	v_mov_b32_e32 v47, v2
	v_mov_b32_e32 v48, v2
	v_mov_b32_e32 v49, v2
	v_mov_b32_e32 v58, v2
	v_mov_b32_e32 v59, v2
	v_mov_b32_e32 v60, v2
	v_mov_b32_e32 v61, v2
	v_mov_b32_e32 v62, v2
	v_mov_b32_e32 v63, v2
	v_mov_b32_e32 v64, v2
	v_mov_b32_e32 v65, v2
	v_mov_b32_e32 v66, v2
	v_mov_b32_e32 v67, v2
	v_mov_b32_e32 v68, v2
	v_mov_b32_e32 v69, v2
	v_mov_b32_e32 v70, v2
	v_mov_b32_e32 v71, v2
	v_mov_b32_e32 v72, v2
	v_mov_b32_e32 v73, v2
	v_mov_b32_e32 v82, v2
	v_mov_b32_e32 v83, v2
	v_mov_b32_e32 v84, v2
	v_mov_b32_e32 v85, v2
	v_mov_b32_e32 v86, v2
	v_mov_b32_e32 v87, v2
	v_mov_b32_e32 v88, v2
	v_mov_b32_e32 v89, v2
	v_mov_b32_e32 v98, v2
	v_mov_b32_e32 v99, v2
	v_mov_b32_e32 v100, v2
	v_mov_b32_e32 v101, v2
	v_mov_b32_e32 v102, v2
	v_mov_b32_e32 v103, v2
	v_mov_b32_e32 v104, v2
	v_mov_b32_e32 v105, v2
	v_mov_b32_e32 v114, v2
	v_mov_b32_e32 v115, v2
	v_mov_b32_e32 v116, v2
	v_mov_b32_e32 v117, v2
	v_mov_b32_e32 v118, v2
	v_mov_b32_e32 v119, v2
	v_mov_b32_e32 v120, v2
	v_mov_b32_e32 v121, v2
	v_mov_b32_e32 v74, v2
	v_mov_b32_e32 v75, v2
	v_mov_b32_e32 v76, v2
	v_mov_b32_e32 v77, v2
	v_mov_b32_e32 v78, v2
	v_mov_b32_e32 v79, v2
	v_mov_b32_e32 v80, v2
	v_mov_b32_e32 v81, v2
	v_mov_b32_e32 v90, v2
	v_mov_b32_e32 v91, v2
	v_mov_b32_e32 v92, v2
	v_mov_b32_e32 v93, v2
	v_mov_b32_e32 v94, v2
	v_mov_b32_e32 v95, v2
	v_mov_b32_e32 v96, v2
	v_mov_b32_e32 v97, v2
	v_mov_b32_e32 v106, v2
	v_mov_b32_e32 v107, v2
	v_mov_b32_e32 v108, v2
	v_mov_b32_e32 v109, v2
	v_mov_b32_e32 v110, v2
	v_mov_b32_e32 v111, v2
	v_mov_b32_e32 v112, v2
	v_mov_b32_e32 v113, v2
	v_mov_b32_e32 v122, v2
	v_mov_b32_e32 v123, v2
	v_mov_b32_e32 v124, v2
	v_mov_b32_e32 v125, v2
	v_mov_b32_e32 v126, v2
	v_mov_b32_e32 v127, v2
	v_mov_b32_e32 v128, v2
	v_mov_b32_e32 v129, v2
	s_branch .LBB0_430
.Lpeel_G67:
	s_add_u32 s36, s34, 0xfffe0080
	s_addc_u32 s37, s35, -1
	s_add_i32 s49, 0, 0x10000
	s_cmp_eq_u32 s48, 4
	s_cselect_b32 s39, s7, s37
	s_cselect_b32 s38, s9, s36
	s_cselect_b32 s37, s21, s45
	s_cselect_b32 s36, s25, s27
	s_add_i32 s61, 0, 0x14000
	v_add_u32_e32 v142, s49, v216
	v_add_u32_e32 v158, s61, v216
	ds_read_b128 v[130:133], v142
	ds_read_b128 v[134:137], v142 offset:1024
	ds_read_b128 v[138:141], v142 offset:2048
	ds_read_b128 v[142:145], v142 offset:3072
	ds_read_b128 v[146:149], v158
	ds_read_b128 v[150:153], v158 offset:1024
	ds_read_b128 v[154:157], v158 offset:2048
	ds_read_b128 v[158:161], v158 offset:3072
	v_lshl_add_u64 v[202:203], s[34:35], 0, v[210:211]
	s_add_i32 m0, s87, 0xc000
	ds_read_b128 v[162:165], v221
	ds_read_b128 v[166:169], v221 offset:1024
	ds_read_b128 v[170:173], v221 offset:2048
	ds_read_b128 v[174:177], v221 offset:3072
	ds_read_b128 v[178:181], v221 offset:4096
	ds_read_b128 v[182:185], v221 offset:5120
	ds_read_b128 v[186:189], v221 offset:6144
	ds_read_b128 v[190:193], v221 offset:7168
	global_load_lds_dwordx4 v[202:203], off
	v_lshl_add_u64 v[202:203], s[34:35], 0, v[208:209]
	s_add_i32 m0, s87, 0xe000
	s_nop 0
	global_load_lds_dwordx4 v[202:203], off
	s_waitcnt vmcnt(24)
	s_waitcnt lgkmcnt(0)
	s_barrier
	s_setprio 1
	s_waitcnt lgkmcnt(0)
	v_mfma_f32_16x16x32_bf16 v[126:129], v[130:133], v[162:165], 0
	v_mfma_f32_16x16x32_bf16 v[122:125], v[138:141], v[162:165], 0
	v_mfma_f32_16x16x32_bf16 v[110:113], v[130:133], v[170:173], 0
	v_mfma_f32_16x16x32_bf16 v[106:109], v[138:141], v[170:173], 0
	v_mfma_f32_16x16x32_bf16 v[94:97], v[130:133], v[178:181], 0
	v_mfma_f32_16x16x32_bf16 v[90:93], v[138:141], v[178:181], 0
	v_mfma_f32_16x16x32_bf16 v[78:81], v[130:133], v[186:189], 0
	v_mfma_f32_16x16x32_bf16 v[74:77], v[138:141], v[186:189], 0
	v_mfma_f32_16x16x32_bf16 v[126:129], v[134:137], v[166:169], v[126:129]
	v_mfma_f32_16x16x32_bf16 v[122:125], v[142:145], v[166:169], v[122:125]
	v_mfma_f32_16x16x32_bf16 v[110:113], v[134:137], v[174:177], v[110:113]
	v_mfma_f32_16x16x32_bf16 v[106:109], v[142:145], v[174:177], v[106:109]
	v_mfma_f32_16x16x32_bf16 v[94:97], v[134:137], v[182:185], v[94:97]
	v_mfma_f32_16x16x32_bf16 v[90:93], v[142:145], v[182:185], v[90:93]
	v_mfma_f32_16x16x32_bf16 v[78:81], v[134:137], v[190:193], v[78:81]
	v_mfma_f32_16x16x32_bf16 v[74:77], v[142:145], v[190:193], v[74:77]
	s_setprio 0
	s_setprio 1
	v_mfma_f32_16x16x32_bf16 v[118:121], v[146:149], v[162:165], 0
	v_mfma_f32_16x16x32_bf16 v[114:117], v[154:157], v[162:165], 0
	v_mfma_f32_16x16x32_bf16 v[102:105], v[146:149], v[170:173], 0
	v_mfma_f32_16x16x32_bf16 v[98:101], v[154:157], v[170:173], 0
	v_mfma_f32_16x16x32_bf16 v[86:89], v[146:149], v[178:181], 0
	v_mfma_f32_16x16x32_bf16 v[82:85], v[154:157], v[178:181], 0
	v_mfma_f32_16x16x32_bf16 v[70:73], v[146:149], v[186:189], 0
	v_mfma_f32_16x16x32_bf16 v[66:69], v[154:157], v[186:189], 0
	v_mfma_f32_16x16x32_bf16 v[118:121], v[150:153], v[166:169], v[118:121]
	v_mfma_f32_16x16x32_bf16 v[114:117], v[158:161], v[166:169], v[114:117]
	v_mfma_f32_16x16x32_bf16 v[102:105], v[150:153], v[174:177], v[102:105]
	v_mfma_f32_16x16x32_bf16 v[98:101], v[158:161], v[174:177], v[98:101]
	v_mfma_f32_16x16x32_bf16 v[86:89], v[150:153], v[182:185], v[86:89]
	v_mfma_f32_16x16x32_bf16 v[82:85], v[158:161], v[182:185], v[82:85]
	v_mfma_f32_16x16x32_bf16 v[70:73], v[150:153], v[190:193], v[70:73]
	v_mfma_f32_16x16x32_bf16 v[66:69], v[158:161], v[190:193], v[66:69]
	s_setprio 0
	s_barrier
	s_add_i32 s49, s49, s86
	v_lshl_add_u64 v[202:203], s[36:37], 0, v[194:195]
	s_mov_b32 m0, s49
	ds_read_b128 v[162:165], v221 offset:16384
	ds_read_b128 v[166:169], v221 offset:17408
	ds_read_b128 v[170:173], v221 offset:18432
	ds_read_b128 v[174:177], v221 offset:19456
	ds_read_b128 v[178:181], v221 offset:20480
	ds_read_b128 v[182:185], v221 offset:21504
	ds_read_b128 v[186:189], v221 offset:22528
	ds_read_b128 v[190:193], v221 offset:23552
	global_load_lds_dwordx4 v[202:203], off
	s_add_i32 m0, s49, 0x2000
	s_add_u32 s94, s36, 0x20000
	v_lshl_add_u64 v[204:205], s[36:37], 0, v[196:197]
	s_addc_u32 s95, s37, 0
	s_add_i32 s49, s61, s86
	global_load_lds_dwordx4 v[204:205], off
	v_lshl_add_u64 v[206:207], s[94:95], 0, v[194:195]
	s_mov_b32 m0, s49
	v_lshl_add_u64 v[222:223], s[38:39], 0, v[196:197]
	global_load_lds_dwordx4 v[206:207], off
	v_lshl_add_u64 v[206:207], s[94:95], 0, v[196:197]
	s_add_i32 m0, s49, 0x2000
	s_nop 0
	global_load_lds_dwordx4 v[206:207], off
	v_lshl_add_u64 v[206:207], s[38:39], 0, v[194:195]
	s_mov_b32 m0, s87
	s_nop 0
	global_load_lds_dwordx4 v[206:207], off
	s_mov_b32 m0, s68
	s_nop 0
	global_load_lds_dwordx4 v[222:223], off
	s_waitcnt vmcnt(24)
	s_waitcnt lgkmcnt(0)
	s_barrier
	s_setprio 1
	s_waitcnt lgkmcnt(0)
	v_mfma_f32_16x16x32_bf16 v[62:65], v[130:133], v[162:165], 0
	v_mfma_f32_16x16x32_bf16 v[58:61], v[138:141], v[162:165], 0
	v_mfma_f32_16x16x32_bf16 v[46:49], v[130:133], v[170:173], 0
	v_mfma_f32_16x16x32_bf16 v[42:45], v[138:141], v[170:173], 0
	v_mfma_f32_16x16x32_bf16 v[30:33], v[130:133], v[178:181], 0
	v_mfma_f32_16x16x32_bf16 v[26:29], v[138:141], v[178:181], 0
	v_mfma_f32_16x16x32_bf16 v[14:17], v[130:133], v[186:189], 0
	v_mfma_f32_16x16x32_bf16 v[10:13], v[138:141], v[186:189], 0
	v_mfma_f32_16x16x32_bf16 v[62:65], v[134:137], v[166:169], v[62:65]
	v_mfma_f32_16x16x32_bf16 v[58:61], v[142:145], v[166:169], v[58:61]
	v_mfma_f32_16x16x32_bf16 v[46:49], v[134:137], v[174:177], v[46:49]
	v_mfma_f32_16x16x32_bf16 v[42:45], v[142:145], v[174:177], v[42:45]
	v_mfma_f32_16x16x32_bf16 v[30:33], v[134:137], v[182:185], v[30:33]
	v_mfma_f32_16x16x32_bf16 v[26:29], v[142:145], v[182:185], v[26:29]
	v_mfma_f32_16x16x32_bf16 v[14:17], v[134:137], v[190:193], v[14:17]
	v_mfma_f32_16x16x32_bf16 v[10:13], v[142:145], v[190:193], v[10:13]
	s_setprio 0
	s_setprio 1
	v_mfma_f32_16x16x32_bf16 v[54:57], v[146:149], v[162:165], 0
	v_mfma_f32_16x16x32_bf16 v[50:53], v[154:157], v[162:165], 0
	v_mfma_f32_16x16x32_bf16 v[38:41], v[146:149], v[170:173], 0
	v_mfma_f32_16x16x32_bf16 v[34:37], v[154:157], v[170:173], 0
	v_mfma_f32_16x16x32_bf16 v[22:25], v[146:149], v[178:181], 0
	v_mfma_f32_16x16x32_bf16 v[18:21], v[154:157], v[178:181], 0
	v_mfma_f32_16x16x32_bf16 v[6:9], v[146:149], v[186:189], 0
	v_mfma_f32_16x16x32_bf16 v[2:5], v[154:157], v[186:189], 0
	v_mfma_f32_16x16x32_bf16 v[54:57], v[150:153], v[166:169], v[54:57]
	v_mfma_f32_16x16x32_bf16 v[50:53], v[158:161], v[166:169], v[50:53]
	v_mfma_f32_16x16x32_bf16 v[38:41], v[150:153], v[174:177], v[38:41]
	v_mfma_f32_16x16x32_bf16 v[34:37], v[158:161], v[174:177], v[34:37]
	v_mfma_f32_16x16x32_bf16 v[22:25], v[150:153], v[182:185], v[22:25]
	v_mfma_f32_16x16x32_bf16 v[18:21], v[158:161], v[182:185], v[18:21]
	v_mfma_f32_16x16x32_bf16 v[6:9], v[150:153], v[190:193], v[6:9]
	v_mfma_f32_16x16x32_bf16 v[2:5], v[158:161], v[190:193], v[2:5]
	s_setprio 0
	s_barrier
	s_add_i32 s49, 0, 0x18000
	s_add_i32 s61, 0, 0x1c000
	v_add_u32_e32 v142, s49, v216
	v_add_u32_e32 v158, s61, v216
	ds_read_b128 v[130:133], v142
	ds_read_b128 v[134:137], v142 offset:1024
	ds_read_b128 v[138:141], v142 offset:2048
	ds_read_b128 v[142:145], v142 offset:3072
	ds_read_b128 v[146:149], v158
	ds_read_b128 v[150:153], v158 offset:1024
	ds_read_b128 v[154:157], v158 offset:2048
	ds_read_b128 v[158:161], v158 offset:3072
	s_add_u32 s38, s38, 0x20000
	s_addc_u32 s39, s39, 0
	s_mov_b32 m0, s69
	v_lshl_add_u64 v[226:227], s[38:39], 0, v[194:195]
	ds_read_b128 v[162:165], v221 offset:32768
	ds_read_b128 v[166:169], v221 offset:33792
	ds_read_b128 v[170:173], v221 offset:34816
	ds_read_b128 v[174:177], v221 offset:35840
	ds_read_b128 v[178:181], v221 offset:36864
	ds_read_b128 v[182:185], v221 offset:37888
	ds_read_b128 v[186:189], v221 offset:38912
	ds_read_b128 v[190:193], v221 offset:39936
	global_load_lds_dwordx4 v[226:227], off
	v_lshl_add_u64 v[226:227], s[38:39], 0, v[196:197]
	s_mov_b32 m0, s70
	s_nop 0
	global_load_lds_dwordx4 v[226:227], off
	s_waitcnt vmcnt(8)
	s_waitcnt lgkmcnt(0)
	s_barrier
	s_setprio 1
	s_waitcnt lgkmcnt(0)
	v_mfma_f32_16x16x32_bf16 v[126:129], v[130:133], v[162:165], v[126:129]
	v_mfma_f32_16x16x32_bf16 v[122:125], v[138:141], v[162:165], v[122:125]
	v_mfma_f32_16x16x32_bf16 v[110:113], v[130:133], v[170:173], v[110:113]
	v_mfma_f32_16x16x32_bf16 v[106:109], v[138:141], v[170:173], v[106:109]
	v_mfma_f32_16x16x32_bf16 v[94:97], v[130:133], v[178:181], v[94:97]
	v_mfma_f32_16x16x32_bf16 v[90:93], v[138:141], v[178:181], v[90:93]
	v_mfma_f32_16x16x32_bf16 v[78:81], v[130:133], v[186:189], v[78:81]
	v_mfma_f32_16x16x32_bf16 v[74:77], v[138:141], v[186:189], v[74:77]
	v_mfma_f32_16x16x32_bf16 v[126:129], v[134:137], v[166:169], v[126:129]
	v_mfma_f32_16x16x32_bf16 v[122:125], v[142:145], v[166:169], v[122:125]
	v_mfma_f32_16x16x32_bf16 v[110:113], v[134:137], v[174:177], v[110:113]
	v_mfma_f32_16x16x32_bf16 v[106:109], v[142:145], v[174:177], v[106:109]
	v_mfma_f32_16x16x32_bf16 v[94:97], v[134:137], v[182:185], v[94:97]
	v_mfma_f32_16x16x32_bf16 v[90:93], v[142:145], v[182:185], v[90:93]
	v_mfma_f32_16x16x32_bf16 v[78:81], v[134:137], v[190:193], v[78:81]
	v_mfma_f32_16x16x32_bf16 v[74:77], v[142:145], v[190:193], v[74:77]
	s_setprio 0
	s_setprio 1
	v_mfma_f32_16x16x32_bf16 v[118:121], v[146:149], v[162:165], v[118:121]
	v_mfma_f32_16x16x32_bf16 v[114:117], v[154:157], v[162:165], v[114:117]
	v_mfma_f32_16x16x32_bf16 v[102:105], v[146:149], v[170:173], v[102:105]
	v_mfma_f32_16x16x32_bf16 v[98:101], v[154:157], v[170:173], v[98:101]
	v_mfma_f32_16x16x32_bf16 v[86:89], v[146:149], v[178:181], v[86:89]
	v_mfma_f32_16x16x32_bf16 v[82:85], v[154:157], v[178:181], v[82:85]
	v_mfma_f32_16x16x32_bf16 v[70:73], v[146:149], v[186:189], v[70:73]
	v_mfma_f32_16x16x32_bf16 v[66:69], v[154:157], v[186:189], v[66:69]
	v_mfma_f32_16x16x32_bf16 v[118:121], v[150:153], v[166:169], v[118:121]
	v_mfma_f32_16x16x32_bf16 v[114:117], v[158:161], v[166:169], v[114:117]
	v_mfma_f32_16x16x32_bf16 v[102:105], v[150:153], v[174:177], v[102:105]
	v_mfma_f32_16x16x32_bf16 v[98:101], v[158:161], v[174:177], v[98:101]
	v_mfma_f32_16x16x32_bf16 v[86:89], v[150:153], v[182:185], v[86:89]
	v_mfma_f32_16x16x32_bf16 v[82:85], v[158:161], v[182:185], v[82:85]
	v_mfma_f32_16x16x32_bf16 v[70:73], v[150:153], v[190:193], v[70:73]
	v_mfma_f32_16x16x32_bf16 v[66:69], v[158:161], v[190:193], v[66:69]
	s_setprio 0
	s_barrier
	s_add_i32 s38, s49, s86
	v_lshl_add_u64 v[202:203], v[202:203], 0, s[54:55]
	s_mov_b32 m0, s38
	ds_read_b128 v[162:165], v221 offset:49152
	ds_read_b128 v[166:169], v221 offset:50176
	ds_read_b128 v[170:173], v221 offset:51200
	ds_read_b128 v[174:177], v221 offset:52224
	ds_read_b128 v[178:181], v221 offset:53248
	ds_read_b128 v[182:185], v221 offset:54272
	ds_read_b128 v[186:189], v221 offset:55296
	ds_read_b128 v[190:193], v221 offset:56320
	global_load_lds_dwordx4 v[202:203], off
	s_add_i32 m0, s38, 0x2000
	s_add_u32 s36, s36, 0x20080
	v_lshl_add_u64 v[202:203], v[204:205], 0, s[54:55]
	s_addc_u32 s37, s37, 0
	s_add_i32 s38, s61, s86
	global_load_lds_dwordx4 v[202:203], off
	v_lshl_add_u64 v[202:203], s[36:37], 0, v[194:195]
	s_mov_b32 m0, s38
	s_nop 0
	global_load_lds_dwordx4 v[202:203], off
	v_lshl_add_u64 v[202:203], s[36:37], 0, v[196:197]
	s_add_i32 m0, s38, 0x2000
	s_nop 0
	global_load_lds_dwordx4 v[202:203], off
	v_lshl_add_u64 v[202:203], v[206:207], 0, s[54:55]
	s_mov_b32 m0, s73
	s_nop 0
	global_load_lds_dwordx4 v[202:203], off
	v_lshl_add_u64 v[202:203], v[222:223], 0, s[54:55]
	s_mov_b32 m0, s89
	s_nop 0
	global_load_lds_dwordx4 v[202:203], off
	s_waitcnt vmcnt(8)
	s_waitcnt lgkmcnt(0)
	s_barrier
	s_setprio 1
	s_waitcnt lgkmcnt(0)
	v_mfma_f32_16x16x32_bf16 v[62:65], v[130:133], v[162:165], v[62:65]
	v_mfma_f32_16x16x32_bf16 v[58:61], v[138:141], v[162:165], v[58:61]
	v_mfma_f32_16x16x32_bf16 v[46:49], v[130:133], v[170:173], v[46:49]
	v_mfma_f32_16x16x32_bf16 v[42:45], v[138:141], v[170:173], v[42:45]
	v_mfma_f32_16x16x32_bf16 v[30:33], v[130:133], v[178:181], v[30:33]
	v_mfma_f32_16x16x32_bf16 v[26:29], v[138:141], v[178:181], v[26:29]
	v_mfma_f32_16x16x32_bf16 v[14:17], v[130:133], v[186:189], v[14:17]
	v_mfma_f32_16x16x32_bf16 v[10:13], v[138:141], v[186:189], v[10:13]
	v_mfma_f32_16x16x32_bf16 v[62:65], v[134:137], v[166:169], v[62:65]
	v_mfma_f32_16x16x32_bf16 v[58:61], v[142:145], v[166:169], v[58:61]
	v_mfma_f32_16x16x32_bf16 v[46:49], v[134:137], v[174:177], v[46:49]
	v_mfma_f32_16x16x32_bf16 v[42:45], v[142:145], v[174:177], v[42:45]
	v_mfma_f32_16x16x32_bf16 v[30:33], v[134:137], v[182:185], v[30:33]
	v_mfma_f32_16x16x32_bf16 v[26:29], v[142:145], v[182:185], v[26:29]
	v_mfma_f32_16x16x32_bf16 v[14:17], v[134:137], v[190:193], v[14:17]
	v_mfma_f32_16x16x32_bf16 v[10:13], v[142:145], v[190:193], v[10:13]
	s_setprio 0
	s_setprio 1
	v_mfma_f32_16x16x32_bf16 v[54:57], v[146:149], v[162:165], v[54:57]
	v_mfma_f32_16x16x32_bf16 v[50:53], v[154:157], v[162:165], v[50:53]
	v_mfma_f32_16x16x32_bf16 v[38:41], v[146:149], v[170:173], v[38:41]
	v_mfma_f32_16x16x32_bf16 v[34:37], v[154:157], v[170:173], v[34:37]
	v_mfma_f32_16x16x32_bf16 v[22:25], v[146:149], v[178:181], v[22:25]
	v_mfma_f32_16x16x32_bf16 v[18:21], v[154:157], v[178:181], v[18:21]
	v_mfma_f32_16x16x32_bf16 v[6:9], v[146:149], v[186:189], v[6:9]
	v_mfma_f32_16x16x32_bf16 v[2:5], v[154:157], v[186:189], v[2:5]
	v_mfma_f32_16x16x32_bf16 v[54:57], v[150:153], v[166:169], v[54:57]
	v_mfma_f32_16x16x32_bf16 v[50:53], v[158:161], v[166:169], v[50:53]
	v_mfma_f32_16x16x32_bf16 v[38:41], v[150:153], v[174:177], v[38:41]
	v_mfma_f32_16x16x32_bf16 v[34:37], v[158:161], v[174:177], v[34:37]
	v_mfma_f32_16x16x32_bf16 v[22:25], v[150:153], v[182:185], v[22:25]
	v_mfma_f32_16x16x32_bf16 v[18:21], v[158:161], v[182:185], v[18:21]
	v_mfma_f32_16x16x32_bf16 v[6:9], v[150:153], v[190:193], v[6:9]
	v_mfma_f32_16x16x32_bf16 v[2:5], v[158:161], v[190:193], v[2:5]
	s_setprio 0
	s_barrier
	s_add_i32 s48, s48, 2
	s_add_u32 s27, s27, 0x100
	s_addc_u32 s45, s45, 0
	s_add_u32 s34, s34, 0x100
	s_addc_u32 s35, s35, 0
	s_cmp_gt_u32 s48, 5
	s_cbranch_scc1 .Lpeel_exit_G67

.LBB0_604:
	s_ashr_i32 s35, s34, 31
	s_lshl_b64 s[36:37], s[34:35], 20
	s_add_u32 s36, s73, s36
	s_addc_u32 s37, s89, s37
	s_and_b64 s[38:39], s[6:7], exec
	s_cselect_b32 s11, s37, s81
	s_cselect_b32 s35, s36, s80
	s_ashr_i32 s31, s30, 31
	s_lshl_b64 s[38:39], s[30:31], 20
	s_add_u32 s38, s97, s38
	s_addc_u32 s39, s65, s39
	s_and_b64 s[82:83], s[6:7], exec
	s_cselect_b32 s31, s39, s9
	s_cselect_b32 s79, s38, s8
	s_add_u32 s84, s8, 0x100
	s_addc_u32 s85, s9, 0
	s_add_u32 s8, s80, 0x80080
	s_addc_u32 s9, s81, 0
	s_mov_b32 s86, -2
	s_cmp_eq_u32 s99, 0
	s_cbranch_scc0 .Lpeel_G1
	v_mov_b32_e32 v2, 0
	v_mov_b32_e32 v3, v2
	v_mov_b32_e32 v4, v2
	v_mov_b32_e32 v5, v2
	v_mov_b32_e32 v6, v2
	v_mov_b32_e32 v7, v2
	v_mov_b32_e32 v8, v2
	v_mov_b32_e32 v9, v2
	v_mov_b32_e32 v18, v2
	v_mov_b32_e32 v19, v2
	v_mov_b32_e32 v20, v2
	v_mov_b32_e32 v21, v2
	v_mov_b32_e32 v22, v2
	v_mov_b32_e32 v23, v2
	v_mov_b32_e32 v24, v2
	v_mov_b32_e32 v25, v2
	v_mov_b32_e32 v34, v2
	v_mov_b32_e32 v35, v2
	v_mov_b32_e32 v36, v2
	v_mov_b32_e32 v37, v2
	v_mov_b32_e32 v38, v2
	v_mov_b32_e32 v39, v2
	v_mov_b32_e32 v40, v2
	v_mov_b32_e32 v41, v2
	v_mov_b32_e32 v50, v2
	v_mov_b32_e32 v51, v2
	v_mov_b32_e32 v52, v2
	v_mov_b32_e32 v53, v2
	v_mov_b32_e32 v54, v2
	v_mov_b32_e32 v55, v2
	v_mov_b32_e32 v56, v2
	v_mov_b32_e32 v57, v2
	v_mov_b32_e32 v10, v2
	v_mov_b32_e32 v11, v2
	v_mov_b32_e32 v12, v2
	v_mov_b32_e32 v13, v2
	v_mov_b32_e32 v14, v2
	v_mov_b32_e32 v15, v2
	v_mov_b32_e32 v16, v2
	v_mov_b32_e32 v17, v2
	v_mov_b32_e32 v26, v2
	v_mov_b32_e32 v27, v2
	v_mov_b32_e32 v28, v2
	v_mov_b32_e32 v29, v2
	v_mov_b32_e32 v30, v2
	v_mov_b32_e32 v31, v2
	v_mov_b32_e32 v32, v2
	v_mov_b32_e32 v33, v2
	v_mov_b32_e32 v42, v2
	v_mov_b32_e32 v43, v2
	v_mov_b32_e32 v44, v2
	v_mov_b32_e32 v45, v2
	v_mov_b32_e32 v46, v2
	v_mov_b32_e32 v47, v2
	v_mov_b32_e32 v48, v2
	v_mov_b32_e32 v49, v2
	v_mov_b32_e32 v58, v2
	v_mov_b32_e32 v59, v2
	v_mov_b32_e32 v60, v2
	v_mov_b32_e32 v61, v2
	v_mov_b32_e32 v62, v2
	v_mov_b32_e32 v63, v2
	v_mov_b32_e32 v64, v2
	v_mov_b32_e32 v65, v2
	v_mov_b32_e32 v66, v2
	v_mov_b32_e32 v67, v2
	v_mov_b32_e32 v68, v2
	v_mov_b32_e32 v69, v2
	v_mov_b32_e32 v70, v2
	v_mov_b32_e32 v71, v2
	v_mov_b32_e32 v72, v2
	v_mov_b32_e32 v73, v2
	v_mov_b32_e32 v82, v2
	v_mov_b32_e32 v83, v2
	v_mov_b32_e32 v84, v2
	v_mov_b32_e32 v85, v2
	v_mov_b32_e32 v86, v2
	v_mov_b32_e32 v87, v2
	v_mov_b32_e32 v88, v2
	v_mov_b32_e32 v89, v2
	v_mov_b32_e32 v98, v2
	v_mov_b32_e32 v99, v2
	v_mov_b32_e32 v100, v2
	v_mov_b32_e32 v101, v2
	v_mov_b32_e32 v102, v2
	v_mov_b32_e32 v103, v2
	v_mov_b32_e32 v104, v2
	v_mov_b32_e32 v105, v2
	v_mov_b32_e32 v114, v2
	v_mov_b32_e32 v115, v2
	v_mov_b32_e32 v116, v2
	v_mov_b32_e32 v117, v2
	v_mov_b32_e32 v118, v2
	v_mov_b32_e32 v119, v2
	v_mov_b32_e32 v120, v2
	v_mov_b32_e32 v121, v2
	v_mov_b32_e32 v74, v2
	v_mov_b32_e32 v75, v2
	v_mov_b32_e32 v76, v2
	v_mov_b32_e32 v77, v2
	v_mov_b32_e32 v78, v2
	v_mov_b32_e32 v79, v2
	v_mov_b32_e32 v80, v2
	v_mov_b32_e32 v81, v2
	v_mov_b32_e32 v90, v2
	v_mov_b32_e32 v91, v2
	v_mov_b32_e32 v92, v2
	v_mov_b32_e32 v93, v2
	v_mov_b32_e32 v94, v2
	v_mov_b32_e32 v95, v2
	v_mov_b32_e32 v96, v2
	v_mov_b32_e32 v97, v2
	v_mov_b32_e32 v106, v2
	v_mov_b32_e32 v107, v2
	v_mov_b32_e32 v108, v2
	v_mov_b32_e32 v109, v2
	v_mov_b32_e32 v110, v2
	v_mov_b32_e32 v111, v2
	v_mov_b32_e32 v112, v2
	v_mov_b32_e32 v113, v2
	v_mov_b32_e32 v122, v2
	v_mov_b32_e32 v123, v2
	v_mov_b32_e32 v124, v2
	v_mov_b32_e32 v125, v2
	v_mov_b32_e32 v130, v2
	v_mov_b32_e32 v131, v2
	v_mov_b32_e32 v132, v2
	v_mov_b32_e32 v133, v2
	s_branch .LBB0_605
.Lpeel_G1:
	s_add_u32 s80, s8, 0xfff80080
	s_addc_u32 s81, s9, -1
	s_add_i32 s87, 0, 0x10000
	s_cmp_eq_u32 s86, 28
	s_cselect_b32 s83, s11, s81
	s_cselect_b32 s82, s35, s80
	s_cselect_b32 s81, s31, s85
	s_cselect_b32 s80, s79, s84
	s_add_i32 s92, 0, 0x14000
	v_add_u32_e32 v142, s87, v228
	v_add_u32_e32 v158, s92, v228
	ds_read_b128 v[126:129], v142
	ds_read_b128 v[134:137], v142 offset:1024
	ds_read_b128 v[138:141], v142 offset:2048
	ds_read_b128 v[142:145], v142 offset:3072
	ds_read_b128 v[146:149], v158
	ds_read_b128 v[150:153], v158 offset:1024
	ds_read_b128 v[154:157], v158 offset:2048
	ds_read_b128 v[158:161], v158 offset:3072
	v_lshl_add_u64 v[202:203], s[8:9], 0, v[210:211]
	s_add_i32 m0, s61, 0xc000
	ds_read_b128 v[162:165], v233
	ds_read_b128 v[166:169], v233 offset:1024
	ds_read_b128 v[170:173], v233 offset:2048
	ds_read_b128 v[174:177], v233 offset:3072
	ds_read_b128 v[178:181], v233 offset:4096
	ds_read_b128 v[182:185], v233 offset:5120
	ds_read_b128 v[186:189], v233 offset:6144
	ds_read_b128 v[190:193], v233 offset:7168
	global_load_lds_dwordx4 v[202:203], off
	v_lshl_add_u64 v[202:203], s[8:9], 0, v[208:209]
	s_add_i32 m0, s61, 0xe000
	s_nop 0
	global_load_lds_dwordx4 v[202:203], off
	s_waitcnt vmcnt(24)
	s_waitcnt lgkmcnt(0)
	s_barrier
	s_setprio 1
	s_waitcnt lgkmcnt(0)
	v_mfma_f32_16x16x32_bf16 v[130:133], v[126:129], v[162:165], 0
	v_mfma_f32_16x16x32_bf16 v[122:125], v[138:141], v[162:165], 0
	v_mfma_f32_16x16x32_bf16 v[110:113], v[126:129], v[170:173], 0
	v_mfma_f32_16x16x32_bf16 v[106:109], v[138:141], v[170:173], 0
	v_mfma_f32_16x16x32_bf16 v[94:97], v[126:129], v[178:181], 0
	v_mfma_f32_16x16x32_bf16 v[90:93], v[138:141], v[178:181], 0
	v_mfma_f32_16x16x32_bf16 v[78:81], v[126:129], v[186:189], 0
	v_mfma_f32_16x16x32_bf16 v[74:77], v[138:141], v[186:189], 0
	v_mfma_f32_16x16x32_bf16 v[130:133], v[134:137], v[166:169], v[130:133]
	v_mfma_f32_16x16x32_bf16 v[122:125], v[142:145], v[166:169], v[122:125]
	v_mfma_f32_16x16x32_bf16 v[110:113], v[134:137], v[174:177], v[110:113]
	v_mfma_f32_16x16x32_bf16 v[106:109], v[142:145], v[174:177], v[106:109]
	v_mfma_f32_16x16x32_bf16 v[94:97], v[134:137], v[182:185], v[94:97]
	v_mfma_f32_16x16x32_bf16 v[90:93], v[142:145], v[182:185], v[90:93]
	v_mfma_f32_16x16x32_bf16 v[78:81], v[134:137], v[190:193], v[78:81]
	v_mfma_f32_16x16x32_bf16 v[74:77], v[142:145], v[190:193], v[74:77]
	s_setprio 0
	s_setprio 1
	v_mfma_f32_16x16x32_bf16 v[118:121], v[146:149], v[162:165], 0
	v_mfma_f32_16x16x32_bf16 v[114:117], v[154:157], v[162:165], 0
	v_mfma_f32_16x16x32_bf16 v[102:105], v[146:149], v[170:173], 0
	v_mfma_f32_16x16x32_bf16 v[98:101], v[154:157], v[170:173], 0
	v_mfma_f32_16x16x32_bf16 v[86:89], v[146:149], v[178:181], 0
	v_mfma_f32_16x16x32_bf16 v[82:85], v[154:157], v[178:181], 0
	v_mfma_f32_16x16x32_bf16 v[70:73], v[146:149], v[186:189], 0
	v_mfma_f32_16x16x32_bf16 v[66:69], v[154:157], v[186:189], 0
	v_mfma_f32_16x16x32_bf16 v[118:121], v[150:153], v[166:169], v[118:121]
	v_mfma_f32_16x16x32_bf16 v[114:117], v[158:161], v[166:169], v[114:117]
	v_mfma_f32_16x16x32_bf16 v[102:105], v[150:153], v[174:177], v[102:105]
	v_mfma_f32_16x16x32_bf16 v[98:101], v[158:161], v[174:177], v[98:101]
	v_mfma_f32_16x16x32_bf16 v[86:89], v[150:153], v[182:185], v[86:89]
	v_mfma_f32_16x16x32_bf16 v[82:85], v[158:161], v[182:185], v[82:85]
	v_mfma_f32_16x16x32_bf16 v[70:73], v[150:153], v[190:193], v[70:73]
	v_mfma_f32_16x16x32_bf16 v[66:69], v[158:161], v[190:193], v[66:69]
	s_setprio 0
	s_barrier
	s_add_i32 s87, s87, s95
	v_lshl_add_u64 v[202:203], s[80:81], 0, v[194:195]
	s_mov_b32 m0, s87
	ds_read_b128 v[162:165], v233 offset:16384
	ds_read_b128 v[166:169], v233 offset:17408
	ds_read_b128 v[170:173], v233 offset:18432
	ds_read_b128 v[174:177], v233 offset:19456
	ds_read_b128 v[178:181], v233 offset:20480
	ds_read_b128 v[182:185], v233 offset:21504
	ds_read_b128 v[186:189], v233 offset:22528
	ds_read_b128 v[190:193], v233 offset:23552
	global_load_lds_dwordx4 v[202:203], off
	s_add_i32 m0, s87, 0x2000
	s_add_u32 vcc_lo, s80, 0x80000
	v_lshl_add_u64 v[204:205], s[80:81], 0, v[196:197]
	s_addc_u32 vcc_hi, s81, 0
	s_add_i32 s87, s92, s95
	global_load_lds_dwordx4 v[204:205], off
	v_lshl_add_u64 v[206:207], vcc, 0, v[194:195]
	s_mov_b32 m0, s87
	v_lshl_add_u64 v[214:215], s[82:83], 0, v[196:197]
	global_load_lds_dwordx4 v[206:207], off
	v_lshl_add_u64 v[206:207], vcc, 0, v[196:197]
	s_add_i32 m0, s87, 0x2000
	s_nop 0
	global_load_lds_dwordx4 v[206:207], off
	v_lshl_add_u64 v[206:207], s[82:83], 0, v[194:195]
	s_mov_b32 m0, s61
	s_nop 0
	global_load_lds_dwordx4 v[206:207], off
	s_mov_b32 m0, s44
	s_nop 0
	global_load_lds_dwordx4 v[214:215], off
	s_waitcnt vmcnt(24)
	s_waitcnt lgkmcnt(0)
	s_barrier
	s_setprio 1
	s_waitcnt lgkmcnt(0)
	v_mfma_f32_16x16x32_bf16 v[62:65], v[126:129], v[162:165], 0
	v_mfma_f32_16x16x32_bf16 v[58:61], v[138:141], v[162:165], 0
	v_mfma_f32_16x16x32_bf16 v[46:49], v[126:129], v[170:173], 0
	v_mfma_f32_16x16x32_bf16 v[42:45], v[138:141], v[170:173], 0
	v_mfma_f32_16x16x32_bf16 v[30:33], v[126:129], v[178:181], 0
	v_mfma_f32_16x16x32_bf16 v[26:29], v[138:141], v[178:181], 0
	v_mfma_f32_16x16x32_bf16 v[14:17], v[126:129], v[186:189], 0
	v_mfma_f32_16x16x32_bf16 v[10:13], v[138:141], v[186:189], 0
	v_mfma_f32_16x16x32_bf16 v[62:65], v[134:137], v[166:169], v[62:65]
	v_mfma_f32_16x16x32_bf16 v[58:61], v[142:145], v[166:169], v[58:61]
	v_mfma_f32_16x16x32_bf16 v[46:49], v[134:137], v[174:177], v[46:49]
	v_mfma_f32_16x16x32_bf16 v[42:45], v[142:145], v[174:177], v[42:45]
	v_mfma_f32_16x16x32_bf16 v[30:33], v[134:137], v[182:185], v[30:33]
	v_mfma_f32_16x16x32_bf16 v[26:29], v[142:145], v[182:185], v[26:29]
	v_mfma_f32_16x16x32_bf16 v[14:17], v[134:137], v[190:193], v[14:17]
	v_mfma_f32_16x16x32_bf16 v[10:13], v[142:145], v[190:193], v[10:13]
	s_setprio 0
	s_setprio 1
	v_mfma_f32_16x16x32_bf16 v[54:57], v[146:149], v[162:165], 0
	v_mfma_f32_16x16x32_bf16 v[50:53], v[154:157], v[162:165], 0
	v_mfma_f32_16x16x32_bf16 v[38:41], v[146:149], v[170:173], 0
	v_mfma_f32_16x16x32_bf16 v[34:37], v[154:157], v[170:173], 0
	v_mfma_f32_16x16x32_bf16 v[22:25], v[146:149], v[178:181], 0
	v_mfma_f32_16x16x32_bf16 v[18:21], v[154:157], v[178:181], 0
	v_mfma_f32_16x16x32_bf16 v[6:9], v[146:149], v[186:189], 0
	v_mfma_f32_16x16x32_bf16 v[2:5], v[154:157], v[186:189], 0
	v_mfma_f32_16x16x32_bf16 v[54:57], v[150:153], v[166:169], v[54:57]
	v_mfma_f32_16x16x32_bf16 v[50:53], v[158:161], v[166:169], v[50:53]
	v_mfma_f32_16x16x32_bf16 v[38:41], v[150:153], v[174:177], v[38:41]
	v_mfma_f32_16x16x32_bf16 v[34:37], v[158:161], v[174:177], v[34:37]
	v_mfma_f32_16x16x32_bf16 v[22:25], v[150:153], v[182:185], v[22:25]
	v_mfma_f32_16x16x32_bf16 v[18:21], v[158:161], v[182:185], v[18:21]
	v_mfma_f32_16x16x32_bf16 v[6:9], v[150:153], v[190:193], v[6:9]
	v_mfma_f32_16x16x32_bf16 v[2:5], v[158:161], v[190:193], v[2:5]
	s_setprio 0
	s_barrier
	s_add_i32 s87, 0, 0x18000
	s_add_i32 s92, 0, 0x1c000
	v_add_u32_e32 v142, s87, v228
	v_add_u32_e32 v158, s92, v228
	ds_read_b128 v[126:129], v142
	ds_read_b128 v[134:137], v142 offset:1024
	ds_read_b128 v[138:141], v142 offset:2048
	ds_read_b128 v[142:145], v142 offset:3072
	ds_read_b128 v[146:149], v158
	ds_read_b128 v[150:153], v158 offset:1024
	ds_read_b128 v[154:157], v158 offset:2048
	ds_read_b128 v[158:161], v158 offset:3072
	s_add_u32 s82, s82, 0x80000
	s_addc_u32 s83, s83, 0
	s_mov_b32 m0, s45
	v_lshl_add_u64 v[216:217], s[82:83], 0, v[194:195]
	ds_read_b128 v[162:165], v233 offset:32768
	ds_read_b128 v[166:169], v233 offset:33792
	ds_read_b128 v[170:173], v233 offset:34816
	ds_read_b128 v[174:177], v233 offset:35840
	ds_read_b128 v[178:181], v233 offset:36864
	ds_read_b128 v[182:185], v233 offset:37888
	ds_read_b128 v[186:189], v233 offset:38912
	ds_read_b128 v[190:193], v233 offset:39936
	global_load_lds_dwordx4 v[216:217], off
	v_lshl_add_u64 v[216:217], s[82:83], 0, v[196:197]
	s_mov_b32 m0, s88
	s_nop 0
	global_load_lds_dwordx4 v[216:217], off
	s_waitcnt vmcnt(8)
	s_waitcnt lgkmcnt(0)
	s_barrier
	s_setprio 1
	s_waitcnt lgkmcnt(0)
	v_mfma_f32_16x16x32_bf16 v[130:133], v[126:129], v[162:165], v[130:133]
	v_mfma_f32_16x16x32_bf16 v[122:125], v[138:141], v[162:165], v[122:125]
	v_mfma_f32_16x16x32_bf16 v[110:113], v[126:129], v[170:173], v[110:113]
	v_mfma_f32_16x16x32_bf16 v[106:109], v[138:141], v[170:173], v[106:109]
	v_mfma_f32_16x16x32_bf16 v[94:97], v[126:129], v[178:181], v[94:97]
	v_mfma_f32_16x16x32_bf16 v[90:93], v[138:141], v[178:181], v[90:93]
	v_mfma_f32_16x16x32_bf16 v[78:81], v[126:129], v[186:189], v[78:81]
	v_mfma_f32_16x16x32_bf16 v[74:77], v[138:141], v[186:189], v[74:77]
	v_mfma_f32_16x16x32_bf16 v[130:133], v[134:137], v[166:169], v[130:133]
	v_mfma_f32_16x16x32_bf16 v[122:125], v[142:145], v[166:169], v[122:125]
	v_mfma_f32_16x16x32_bf16 v[110:113], v[134:137], v[174:177], v[110:113]
	v_mfma_f32_16x16x32_bf16 v[106:109], v[142:145], v[174:177], v[106:109]
	v_mfma_f32_16x16x32_bf16 v[94:97], v[134:137], v[182:185], v[94:97]
	v_mfma_f32_16x16x32_bf16 v[90:93], v[142:145], v[182:185], v[90:93]
	v_mfma_f32_16x16x32_bf16 v[78:81], v[134:137], v[190:193], v[78:81]
	v_mfma_f32_16x16x32_bf16 v[74:77], v[142:145], v[190:193], v[74:77]
	s_setprio 0
	s_setprio 1
	v_mfma_f32_16x16x32_bf16 v[118:121], v[146:149], v[162:165], v[118:121]
	v_mfma_f32_16x16x32_bf16 v[114:117], v[154:157], v[162:165], v[114:117]
	v_mfma_f32_16x16x32_bf16 v[102:105], v[146:149], v[170:173], v[102:105]
	v_mfma_f32_16x16x32_bf16 v[98:101], v[154:157], v[170:173], v[98:101]
	v_mfma_f32_16x16x32_bf16 v[86:89], v[146:149], v[178:181], v[86:89]
	v_mfma_f32_16x16x32_bf16 v[82:85], v[154:157], v[178:181], v[82:85]
	v_mfma_f32_16x16x32_bf16 v[70:73], v[146:149], v[186:189], v[70:73]
	v_mfma_f32_16x16x32_bf16 v[66:69], v[154:157], v[186:189], v[66:69]
	v_mfma_f32_16x16x32_bf16 v[118:121], v[150:153], v[166:169], v[118:121]
	v_mfma_f32_16x16x32_bf16 v[114:117], v[158:161], v[166:169], v[114:117]
	v_mfma_f32_16x16x32_bf16 v[102:105], v[150:153], v[174:177], v[102:105]
	v_mfma_f32_16x16x32_bf16 v[98:101], v[158:161], v[174:177], v[98:101]
	v_mfma_f32_16x16x32_bf16 v[86:89], v[150:153], v[182:185], v[86:89]
	v_mfma_f32_16x16x32_bf16 v[82:85], v[158:161], v[182:185], v[82:85]
	v_mfma_f32_16x16x32_bf16 v[70:73], v[150:153], v[190:193], v[70:73]
	v_mfma_f32_16x16x32_bf16 v[66:69], v[158:161], v[190:193], v[66:69]
	s_setprio 0
	s_barrier
	s_add_i32 s82, s87, s95
	v_lshl_add_u64 v[202:203], v[202:203], 0, s[54:55]
	s_mov_b32 m0, s82
	ds_read_b128 v[162:165], v233 offset:49152
	ds_read_b128 v[166:169], v233 offset:50176
	ds_read_b128 v[170:173], v233 offset:51200
	ds_read_b128 v[174:177], v233 offset:52224
	ds_read_b128 v[178:181], v233 offset:53248
	ds_read_b128 v[182:185], v233 offset:54272
	ds_read_b128 v[186:189], v233 offset:55296
	ds_read_b128 v[190:193], v233 offset:56320
	global_load_lds_dwordx4 v[202:203], off
	s_add_i32 m0, s82, 0x2000
	s_add_u32 s80, s80, 0x80080
	v_lshl_add_u64 v[202:203], v[204:205], 0, s[54:55]
	s_addc_u32 s81, s81, 0
	s_add_i32 s82, s92, s95
	global_load_lds_dwordx4 v[202:203], off
	v_lshl_add_u64 v[202:203], s[80:81], 0, v[194:195]
	s_mov_b32 m0, s82
	s_nop 0
	global_load_lds_dwordx4 v[202:203], off
	v_lshl_add_u64 v[202:203], s[80:81], 0, v[196:197]
	s_add_i32 m0, s82, 0x2000
	s_nop 0
	global_load_lds_dwordx4 v[202:203], off
	v_lshl_add_u64 v[202:203], v[206:207], 0, s[54:55]
	s_mov_b32 m0, s48
	s_nop 0
	global_load_lds_dwordx4 v[202:203], off
	v_lshl_add_u64 v[202:203], v[214:215], 0, s[54:55]
	s_mov_b32 m0, s49
	s_nop 0
	global_load_lds_dwordx4 v[202:203], off
	s_waitcnt vmcnt(8)
	s_waitcnt lgkmcnt(0)
	s_barrier
	s_setprio 1
	s_waitcnt lgkmcnt(0)
	v_mfma_f32_16x16x32_bf16 v[62:65], v[126:129], v[162:165], v[62:65]
	v_mfma_f32_16x16x32_bf16 v[58:61], v[138:141], v[162:165], v[58:61]
	v_mfma_f32_16x16x32_bf16 v[46:49], v[126:129], v[170:173], v[46:49]
	v_mfma_f32_16x16x32_bf16 v[42:45], v[138:141], v[170:173], v[42:45]
	v_mfma_f32_16x16x32_bf16 v[30:33], v[126:129], v[178:181], v[30:33]
	v_mfma_f32_16x16x32_bf16 v[26:29], v[138:141], v[178:181], v[26:29]
	v_mfma_f32_16x16x32_bf16 v[14:17], v[126:129], v[186:189], v[14:17]
	v_mfma_f32_16x16x32_bf16 v[10:13], v[138:141], v[186:189], v[10:13]
	v_mfma_f32_16x16x32_bf16 v[62:65], v[134:137], v[166:169], v[62:65]
	v_mfma_f32_16x16x32_bf16 v[58:61], v[142:145], v[166:169], v[58:61]
	v_mfma_f32_16x16x32_bf16 v[46:49], v[134:137], v[174:177], v[46:49]
	v_mfma_f32_16x16x32_bf16 v[42:45], v[142:145], v[174:177], v[42:45]
	v_mfma_f32_16x16x32_bf16 v[30:33], v[134:137], v[182:185], v[30:33]
	v_mfma_f32_16x16x32_bf16 v[26:29], v[142:145], v[182:185], v[26:29]
	v_mfma_f32_16x16x32_bf16 v[14:17], v[134:137], v[190:193], v[14:17]
	v_mfma_f32_16x16x32_bf16 v[10:13], v[142:145], v[190:193], v[10:13]
	s_setprio 0
	s_setprio 1
	v_mfma_f32_16x16x32_bf16 v[54:57], v[146:149], v[162:165], v[54:57]
	v_mfma_f32_16x16x32_bf16 v[50:53], v[154:157], v[162:165], v[50:53]
	v_mfma_f32_16x16x32_bf16 v[38:41], v[146:149], v[170:173], v[38:41]
	v_mfma_f32_16x16x32_bf16 v[34:37], v[154:157], v[170:173], v[34:37]
	v_mfma_f32_16x16x32_bf16 v[22:25], v[146:149], v[178:181], v[22:25]
	v_mfma_f32_16x16x32_bf16 v[18:21], v[154:157], v[178:181], v[18:21]
	v_mfma_f32_16x16x32_bf16 v[6:9], v[146:149], v[186:189], v[6:9]
	v_mfma_f32_16x16x32_bf16 v[2:5], v[154:157], v[186:189], v[2:5]
	v_mfma_f32_16x16x32_bf16 v[54:57], v[150:153], v[166:169], v[54:57]
	v_mfma_f32_16x16x32_bf16 v[50:53], v[158:161], v[166:169], v[50:53]
	v_mfma_f32_16x16x32_bf16 v[38:41], v[150:153], v[174:177], v[38:41]
	v_mfma_f32_16x16x32_bf16 v[34:37], v[158:161], v[174:177], v[34:37]
	v_mfma_f32_16x16x32_bf16 v[22:25], v[150:153], v[182:185], v[22:25]
	v_mfma_f32_16x16x32_bf16 v[18:21], v[158:161], v[182:185], v[18:21]
	v_mfma_f32_16x16x32_bf16 v[6:9], v[150:153], v[190:193], v[6:9]
	v_mfma_f32_16x16x32_bf16 v[2:5], v[158:161], v[190:193], v[2:5]
	s_setprio 0
	s_barrier
	s_add_i32 s86, s86, 2
	s_add_u32 s84, s84, 0x100
	s_addc_u32 s85, s85, 0
	s_add_u32 s8, s8, 0x100
	s_addc_u32 s9, s9, 0
	s_cmp_gt_u32 s86, 29
	s_cbranch_scc1 .Lpeel_exit_G1

.LBB0_1059:
	s_ashr_i32 s19, s18, 31
	s_lshl_b64 s[20:21], s[18:19], 20
	s_add_u32 s20, s67, s20
	s_addc_u32 s21, s78, s21
	s_and_b64 s[22:23], s[4:5], exec
	s_cselect_b32 s19, s21, s29
	s_cselect_b32 s33, s20, s28
	s_ashr_i32 s17, s16, 31
	s_lshl_b64 s[22:23], s[16:17], 20
	s_add_u32 s22, s79, s22
	s_addc_u32 s23, s80, s23
	s_and_b64 s[30:31], s[4:5], exec
	s_cselect_b32 s17, s23, s27
	s_cselect_b32 s44, s22, s26
	s_add_u32 s45, s26, 0x100
	s_addc_u32 s48, s27, 0
	s_add_u32 s26, s28, 0x80080
	s_addc_u32 s27, s29, 0
	s_mov_b32 s49, -2
	s_cmp_eq_u32 s99, 0
	s_cbranch_scc0 .Lpeel_G3
	v_mov_b32_e32 v2, 0
	v_mov_b32_e32 v3, v2
	v_mov_b32_e32 v4, v2
	v_mov_b32_e32 v5, v2
	v_mov_b32_e32 v10, v2
	v_mov_b32_e32 v11, v2
	v_mov_b32_e32 v12, v2
	v_mov_b32_e32 v13, v2
	v_mov_b32_e32 v18, v2
	v_mov_b32_e32 v19, v2
	v_mov_b32_e32 v20, v2
	v_mov_b32_e32 v21, v2
	v_mov_b32_e32 v26, v2
	v_mov_b32_e32 v27, v2
	v_mov_b32_e32 v28, v2
	v_mov_b32_e32 v29, v2
	v_mov_b32_e32 v34, v2
	v_mov_b32_e32 v35, v2
	v_mov_b32_e32 v36, v2
	v_mov_b32_e32 v37, v2
	v_mov_b32_e32 v42, v2
	v_mov_b32_e32 v43, v2
	v_mov_b32_e32 v44, v2
	v_mov_b32_e32 v45, v2
	v_mov_b32_e32 v50, v2
	v_mov_b32_e32 v51, v2
	v_mov_b32_e32 v52, v2
	v_mov_b32_e32 v53, v2
	v_mov_b32_e32 v58, v2
	v_mov_b32_e32 v59, v2
	v_mov_b32_e32 v60, v2
	v_mov_b32_e32 v61, v2
	v_mov_b32_e32 v6, v2
	v_mov_b32_e32 v7, v2
	v_mov_b32_e32 v8, v2
	v_mov_b32_e32 v9, v2
	v_mov_b32_e32 v14, v2
	v_mov_b32_e32 v15, v2
	v_mov_b32_e32 v16, v2
	v_mov_b32_e32 v17, v2
	v_mov_b32_e32 v22, v2
	v_mov_b32_e32 v23, v2
	v_mov_b32_e32 v24, v2
	v_mov_b32_e32 v25, v2
	v_mov_b32_e32 v30, v2
	v_mov_b32_e32 v31, v2
	v_mov_b32_e32 v32, v2
	v_mov_b32_e32 v33, v2
	v_mov_b32_e32 v38, v2
	v_mov_b32_e32 v39, v2
	v_mov_b32_e32 v40, v2
	v_mov_b32_e32 v41, v2
	v_mov_b32_e32 v46, v2
	v_mov_b32_e32 v47, v2
	v_mov_b32_e32 v48, v2
	v_mov_b32_e32 v49, v2
	v_mov_b32_e32 v54, v2
	v_mov_b32_e32 v55, v2
	v_mov_b32_e32 v56, v2
	v_mov_b32_e32 v57, v2
	v_mov_b32_e32 v62, v2
	v_mov_b32_e32 v63, v2
	v_mov_b32_e32 v64, v2
	v_mov_b32_e32 v65, v2
	v_mov_b32_e32 v66, v2
	v_mov_b32_e32 v67, v2
	v_mov_b32_e32 v68, v2
	v_mov_b32_e32 v69, v2
	v_mov_b32_e32 v74, v2
	v_mov_b32_e32 v75, v2
	v_mov_b32_e32 v76, v2
	v_mov_b32_e32 v77, v2
	v_mov_b32_e32 v82, v2
	v_mov_b32_e32 v83, v2
	v_mov_b32_e32 v84, v2
	v_mov_b32_e32 v85, v2
	v_mov_b32_e32 v90, v2
	v_mov_b32_e32 v91, v2
	v_mov_b32_e32 v92, v2
	v_mov_b32_e32 v93, v2
	v_mov_b32_e32 v98, v2
	v_mov_b32_e32 v99, v2
	v_mov_b32_e32 v100, v2
	v_mov_b32_e32 v101, v2
	v_mov_b32_e32 v106, v2
	v_mov_b32_e32 v107, v2
	v_mov_b32_e32 v108, v2
	v_mov_b32_e32 v109, v2
	v_mov_b32_e32 v114, v2
	v_mov_b32_e32 v115, v2
	v_mov_b32_e32 v116, v2
	v_mov_b32_e32 v117, v2
	v_mov_b32_e32 v122, v2
	v_mov_b32_e32 v123, v2
	v_mov_b32_e32 v124, v2
	v_mov_b32_e32 v125, v2
	v_mov_b32_e32 v70, v2
	v_mov_b32_e32 v71, v2
	v_mov_b32_e32 v72, v2
	v_mov_b32_e32 v73, v2
	v_mov_b32_e32 v78, v2
	v_mov_b32_e32 v79, v2
	v_mov_b32_e32 v80, v2
	v_mov_b32_e32 v81, v2
	v_mov_b32_e32 v86, v2
	v_mov_b32_e32 v87, v2
	v_mov_b32_e32 v88, v2
	v_mov_b32_e32 v89, v2
	v_mov_b32_e32 v94, v2
	v_mov_b32_e32 v95, v2
	v_mov_b32_e32 v96, v2
	v_mov_b32_e32 v97, v2
	v_mov_b32_e32 v102, v2
	v_mov_b32_e32 v103, v2
	v_mov_b32_e32 v104, v2
	v_mov_b32_e32 v105, v2
	v_mov_b32_e32 v110, v2
	v_mov_b32_e32 v111, v2
	v_mov_b32_e32 v112, v2
	v_mov_b32_e32 v113, v2
	v_mov_b32_e32 v118, v2
	v_mov_b32_e32 v119, v2
	v_mov_b32_e32 v120, v2
	v_mov_b32_e32 v121, v2
	v_mov_b32_e32 v126, v2
	v_mov_b32_e32 v127, v2
	v_mov_b32_e32 v128, v2
	v_mov_b32_e32 v129, v2
	s_branch .LBB0_1060
.Lpeel_G3:
	s_add_u32 s28, s26, 0xfff80080
	s_addc_u32 s29, s27, -1
	s_add_i32 s61, 0, 0x10000
	s_cmp_eq_u32 s49, 28
	s_cselect_b32 s31, s19, s29
	s_cselect_b32 s30, s33, s28
	v_add_u32_e32 v141, s61, v138
	s_cselect_b32 s29, s17, s48
	s_cselect_b32 s28, s44, s45
	s_add_i32 s73, 0, 0x14000
	ds_read_b128 v[142:145], v141
	ds_read_b128 v[146:149], v141 offset:1024
	ds_read_b128 v[150:153], v141 offset:2048
	ds_read_b128 v[154:157], v141 offset:3072
	v_add_u32_e32 v141, s73, v138
	ds_read_b128 v[158:161], v141
	ds_read_b128 v[162:165], v141 offset:1024
	ds_read_b128 v[166:169], v141 offset:2048
	ds_read_b128 v[170:173], v141 offset:3072
	v_lshl_add_u64 v[206:207], s[26:27], 0, v[134:135]
	s_add_i32 m0, s82, 0xc000
	ds_read_b128 v[174:177], v140
	ds_read_b128 v[178:181], v140 offset:1024
	ds_read_b128 v[182:185], v140 offset:2048
	ds_read_b128 v[186:189], v140 offset:3072
	ds_read_b128 v[190:193], v140 offset:4096
	ds_read_b128 v[194:197], v140 offset:5120
	ds_read_b128 v[198:201], v140 offset:6144
	ds_read_b128 v[202:205], v140 offset:7168
	global_load_lds_dwordx4 v[206:207], off
	v_lshl_add_u64 v[206:207], s[26:27], 0, v[132:133]
	s_add_i32 m0, s82, 0xe000
	s_nop 0
	global_load_lds_dwordx4 v[206:207], off
	s_waitcnt vmcnt(16)
	s_waitcnt lgkmcnt(0)
	s_barrier
	s_setprio 1
	s_waitcnt lgkmcnt(0)
	v_mfma_f32_16x16x32_bf16 v[126:129], v[142:145], v[174:177], 0
	v_mfma_f32_16x16x32_bf16 v[118:121], v[150:153], v[174:177], 0
	v_mfma_f32_16x16x32_bf16 v[110:113], v[142:145], v[182:185], 0
	v_mfma_f32_16x16x32_bf16 v[102:105], v[150:153], v[182:185], 0
	v_mfma_f32_16x16x32_bf16 v[94:97], v[142:145], v[190:193], 0
	v_mfma_f32_16x16x32_bf16 v[86:89], v[150:153], v[190:193], 0
	v_mfma_f32_16x16x32_bf16 v[78:81], v[142:145], v[198:201], 0
	v_mfma_f32_16x16x32_bf16 v[70:73], v[150:153], v[198:201], 0
	v_mfma_f32_16x16x32_bf16 v[126:129], v[146:149], v[178:181], v[126:129]
	v_mfma_f32_16x16x32_bf16 v[118:121], v[154:157], v[178:181], v[118:121]
	v_mfma_f32_16x16x32_bf16 v[110:113], v[146:149], v[186:189], v[110:113]
	v_mfma_f32_16x16x32_bf16 v[102:105], v[154:157], v[186:189], v[102:105]
	v_mfma_f32_16x16x32_bf16 v[94:97], v[146:149], v[194:197], v[94:97]
	v_mfma_f32_16x16x32_bf16 v[86:89], v[154:157], v[194:197], v[86:89]
	v_mfma_f32_16x16x32_bf16 v[78:81], v[146:149], v[202:205], v[78:81]
	v_mfma_f32_16x16x32_bf16 v[70:73], v[154:157], v[202:205], v[70:73]
	s_setprio 0
	s_setprio 1
	v_mfma_f32_16x16x32_bf16 v[122:125], v[158:161], v[174:177], 0
	v_mfma_f32_16x16x32_bf16 v[114:117], v[166:169], v[174:177], 0
	v_mfma_f32_16x16x32_bf16 v[106:109], v[158:161], v[182:185], 0
	v_mfma_f32_16x16x32_bf16 v[98:101], v[166:169], v[182:185], 0
	v_mfma_f32_16x16x32_bf16 v[90:93], v[158:161], v[190:193], 0
	v_mfma_f32_16x16x32_bf16 v[82:85], v[166:169], v[190:193], 0
	v_mfma_f32_16x16x32_bf16 v[74:77], v[158:161], v[198:201], 0
	v_mfma_f32_16x16x32_bf16 v[66:69], v[166:169], v[198:201], 0
	v_mfma_f32_16x16x32_bf16 v[122:125], v[162:165], v[178:181], v[122:125]
	v_mfma_f32_16x16x32_bf16 v[114:117], v[170:173], v[178:181], v[114:117]
	v_mfma_f32_16x16x32_bf16 v[106:109], v[162:165], v[186:189], v[106:109]
	v_mfma_f32_16x16x32_bf16 v[98:101], v[170:173], v[186:189], v[98:101]
	v_mfma_f32_16x16x32_bf16 v[90:93], v[162:165], v[194:197], v[90:93]
	v_mfma_f32_16x16x32_bf16 v[82:85], v[170:173], v[194:197], v[82:85]
	v_mfma_f32_16x16x32_bf16 v[74:77], v[162:165], v[202:205], v[74:77]
	v_mfma_f32_16x16x32_bf16 v[66:69], v[170:173], v[202:205], v[66:69]
	s_setprio 0
	s_barrier
	s_add_i32 s61, s61, s81
	v_lshl_add_u64 v[206:207], s[28:29], 0, v[0:1]
	s_mov_b32 m0, s61
	ds_read_b128 v[174:177], v140 offset:16384
	ds_read_b128 v[178:181], v140 offset:17408
	ds_read_b128 v[182:185], v140 offset:18432
	ds_read_b128 v[186:189], v140 offset:19456
	ds_read_b128 v[190:193], v140 offset:20480
	ds_read_b128 v[194:197], v140 offset:21504
	ds_read_b128 v[198:201], v140 offset:22528
	ds_read_b128 v[202:205], v140 offset:23552
	global_load_lds_dwordx4 v[206:207], off
	s_add_i32 m0, s61, 0x2000
	s_add_u32 s84, s28, 0x80000
	v_lshl_add_u64 v[208:209], s[28:29], 0, v[130:131]
	s_addc_u32 s85, s29, 0
	s_add_i32 s61, s73, s81
	global_load_lds_dwordx4 v[208:209], off
	v_lshl_add_u64 v[210:211], s[84:85], 0, v[0:1]
	s_mov_b32 m0, s61
	v_lshl_add_u64 v[212:213], s[30:31], 0, v[130:131]
	global_load_lds_dwordx4 v[210:211], off
	v_lshl_add_u64 v[210:211], s[84:85], 0, v[130:131]
	s_add_i32 m0, s61, 0x2000
	s_nop 0
	global_load_lds_dwordx4 v[210:211], off
	v_lshl_add_u64 v[210:211], s[30:31], 0, v[0:1]
	s_mov_b32 m0, s82
	s_nop 0
	global_load_lds_dwordx4 v[210:211], off
	s_mov_b32 m0, s68
	s_nop 0
	global_load_lds_dwordx4 v[212:213], off
	s_waitcnt vmcnt(16)
	s_waitcnt lgkmcnt(0)
	s_barrier
	s_setprio 1
	s_waitcnt lgkmcnt(0)
	v_mfma_f32_16x16x32_bf16 v[62:65], v[142:145], v[174:177], 0
	v_mfma_f32_16x16x32_bf16 v[54:57], v[150:153], v[174:177], 0
	v_mfma_f32_16x16x32_bf16 v[46:49], v[142:145], v[182:185], 0
	v_mfma_f32_16x16x32_bf16 v[38:41], v[150:153], v[182:185], 0
	v_mfma_f32_16x16x32_bf16 v[30:33], v[142:145], v[190:193], 0
	v_mfma_f32_16x16x32_bf16 v[22:25], v[150:153], v[190:193], 0
	v_mfma_f32_16x16x32_bf16 v[14:17], v[142:145], v[198:201], 0
	v_mfma_f32_16x16x32_bf16 v[6:9], v[150:153], v[198:201], 0
	v_mfma_f32_16x16x32_bf16 v[62:65], v[146:149], v[178:181], v[62:65]
	v_mfma_f32_16x16x32_bf16 v[54:57], v[154:157], v[178:181], v[54:57]
	v_mfma_f32_16x16x32_bf16 v[46:49], v[146:149], v[186:189], v[46:49]
	v_mfma_f32_16x16x32_bf16 v[38:41], v[154:157], v[186:189], v[38:41]
	v_mfma_f32_16x16x32_bf16 v[30:33], v[146:149], v[194:197], v[30:33]
	v_mfma_f32_16x16x32_bf16 v[22:25], v[154:157], v[194:197], v[22:25]
	v_mfma_f32_16x16x32_bf16 v[14:17], v[146:149], v[202:205], v[14:17]
	v_mfma_f32_16x16x32_bf16 v[6:9], v[154:157], v[202:205], v[6:9]
	s_setprio 0
	s_setprio 1
	v_mfma_f32_16x16x32_bf16 v[58:61], v[158:161], v[174:177], 0
	v_mfma_f32_16x16x32_bf16 v[50:53], v[166:169], v[174:177], 0
	v_mfma_f32_16x16x32_bf16 v[42:45], v[158:161], v[182:185], 0
	v_mfma_f32_16x16x32_bf16 v[34:37], v[166:169], v[182:185], 0
	v_mfma_f32_16x16x32_bf16 v[26:29], v[158:161], v[190:193], 0
	v_mfma_f32_16x16x32_bf16 v[18:21], v[166:169], v[190:193], 0
	v_mfma_f32_16x16x32_bf16 v[10:13], v[158:161], v[198:201], 0
	v_mfma_f32_16x16x32_bf16 v[2:5], v[166:169], v[198:201], 0
	v_mfma_f32_16x16x32_bf16 v[58:61], v[162:165], v[178:181], v[58:61]
	v_mfma_f32_16x16x32_bf16 v[50:53], v[170:173], v[178:181], v[50:53]
	v_mfma_f32_16x16x32_bf16 v[42:45], v[162:165], v[186:189], v[42:45]
	v_mfma_f32_16x16x32_bf16 v[34:37], v[170:173], v[186:189], v[34:37]
	v_mfma_f32_16x16x32_bf16 v[26:29], v[162:165], v[194:197], v[26:29]
	v_mfma_f32_16x16x32_bf16 v[18:21], v[170:173], v[194:197], v[18:21]
	v_mfma_f32_16x16x32_bf16 v[10:13], v[162:165], v[202:205], v[10:13]
	v_mfma_f32_16x16x32_bf16 v[2:5], v[170:173], v[202:205], v[2:5]
	s_setprio 0
	s_barrier
	s_add_i32 s61, 0, 0x18000
	v_add_u32_e32 v141, s61, v138
	s_add_i32 s73, 0, 0x1c000
	ds_read_b128 v[142:145], v141
	ds_read_b128 v[146:149], v141 offset:1024
	ds_read_b128 v[150:153], v141 offset:2048
	ds_read_b128 v[154:157], v141 offset:3072
	v_add_u32_e32 v141, s73, v138
	ds_read_b128 v[158:161], v141
	ds_read_b128 v[162:165], v141 offset:1024
	ds_read_b128 v[166:169], v141 offset:2048
	ds_read_b128 v[170:173], v141 offset:3072
	s_add_u32 s30, s30, 0x80000
	s_addc_u32 s31, s31, 0
	s_mov_b32 m0, s69
	v_lshl_add_u64 v[214:215], s[30:31], 0, v[0:1]
	ds_read_b128 v[174:177], v140 offset:32768
	ds_read_b128 v[178:181], v140 offset:33792
	ds_read_b128 v[182:185], v140 offset:34816
	ds_read_b128 v[186:189], v140 offset:35840
	ds_read_b128 v[190:193], v140 offset:36864
	ds_read_b128 v[194:197], v140 offset:37888
	ds_read_b128 v[198:201], v140 offset:38912
	ds_read_b128 v[202:205], v140 offset:39936
	global_load_lds_dwordx4 v[214:215], off
	v_lshl_add_u64 v[214:215], s[30:31], 0, v[130:131]
	s_mov_b32 m0, s70
	s_nop 0
	global_load_lds_dwordx4 v[214:215], off
	s_waitcnt vmcnt(8)
	s_waitcnt lgkmcnt(0)
	s_barrier
	s_setprio 1
	s_waitcnt lgkmcnt(0)
	v_mfma_f32_16x16x32_bf16 v[126:129], v[142:145], v[174:177], v[126:129]
	v_mfma_f32_16x16x32_bf16 v[118:121], v[150:153], v[174:177], v[118:121]
	v_mfma_f32_16x16x32_bf16 v[110:113], v[142:145], v[182:185], v[110:113]
	v_mfma_f32_16x16x32_bf16 v[102:105], v[150:153], v[182:185], v[102:105]
	v_mfma_f32_16x16x32_bf16 v[94:97], v[142:145], v[190:193], v[94:97]
	v_mfma_f32_16x16x32_bf16 v[86:89], v[150:153], v[190:193], v[86:89]
	v_mfma_f32_16x16x32_bf16 v[78:81], v[142:145], v[198:201], v[78:81]
	v_mfma_f32_16x16x32_bf16 v[70:73], v[150:153], v[198:201], v[70:73]
	v_mfma_f32_16x16x32_bf16 v[126:129], v[146:149], v[178:181], v[126:129]
	v_mfma_f32_16x16x32_bf16 v[118:121], v[154:157], v[178:181], v[118:121]
	v_mfma_f32_16x16x32_bf16 v[110:113], v[146:149], v[186:189], v[110:113]
	v_mfma_f32_16x16x32_bf16 v[102:105], v[154:157], v[186:189], v[102:105]
	v_mfma_f32_16x16x32_bf16 v[94:97], v[146:149], v[194:197], v[94:97]
	v_mfma_f32_16x16x32_bf16 v[86:89], v[154:157], v[194:197], v[86:89]
	v_mfma_f32_16x16x32_bf16 v[78:81], v[146:149], v[202:205], v[78:81]
	v_mfma_f32_16x16x32_bf16 v[70:73], v[154:157], v[202:205], v[70:73]
	s_setprio 0
	s_setprio 1
	v_mfma_f32_16x16x32_bf16 v[122:125], v[158:161], v[174:177], v[122:125]
	v_mfma_f32_16x16x32_bf16 v[114:117], v[166:169], v[174:177], v[114:117]
	v_mfma_f32_16x16x32_bf16 v[106:109], v[158:161], v[182:185], v[106:109]
	v_mfma_f32_16x16x32_bf16 v[98:101], v[166:169], v[182:185], v[98:101]
	v_mfma_f32_16x16x32_bf16 v[90:93], v[158:161], v[190:193], v[90:93]
	v_mfma_f32_16x16x32_bf16 v[82:85], v[166:169], v[190:193], v[82:85]
	v_mfma_f32_16x16x32_bf16 v[74:77], v[158:161], v[198:201], v[74:77]
	v_mfma_f32_16x16x32_bf16 v[66:69], v[166:169], v[198:201], v[66:69]
	v_mfma_f32_16x16x32_bf16 v[122:125], v[162:165], v[178:181], v[122:125]
	v_mfma_f32_16x16x32_bf16 v[114:117], v[170:173], v[178:181], v[114:117]
	v_mfma_f32_16x16x32_bf16 v[106:109], v[162:165], v[186:189], v[106:109]
	v_mfma_f32_16x16x32_bf16 v[98:101], v[170:173], v[186:189], v[98:101]
	v_mfma_f32_16x16x32_bf16 v[90:93], v[162:165], v[194:197], v[90:93]
	v_mfma_f32_16x16x32_bf16 v[82:85], v[170:173], v[194:197], v[82:85]
	v_mfma_f32_16x16x32_bf16 v[74:77], v[162:165], v[202:205], v[74:77]
	v_mfma_f32_16x16x32_bf16 v[66:69], v[170:173], v[202:205], v[66:69]
	s_setprio 0
	s_barrier
	s_add_i32 s30, s61, s81
	v_lshl_add_u64 v[206:207], v[206:207], 0, s[54:55]
	s_mov_b32 m0, s30
	ds_read_b128 v[174:177], v140 offset:49152
	ds_read_b128 v[178:181], v140 offset:50176
	ds_read_b128 v[182:185], v140 offset:51200
	ds_read_b128 v[186:189], v140 offset:52224
	ds_read_b128 v[190:193], v140 offset:53248
	ds_read_b128 v[194:197], v140 offset:54272
	ds_read_b128 v[198:201], v140 offset:55296
	ds_read_b128 v[202:205], v140 offset:56320
	global_load_lds_dwordx4 v[206:207], off
	s_add_i32 m0, s30, 0x2000
	s_add_u32 s28, s28, 0x80080
	v_lshl_add_u64 v[206:207], v[208:209], 0, s[54:55]
	s_addc_u32 s29, s29, 0
	s_add_i32 s30, s73, s81
	global_load_lds_dwordx4 v[206:207], off
	v_lshl_add_u64 v[206:207], s[28:29], 0, v[0:1]
	s_mov_b32 m0, s30
	s_nop 0
	global_load_lds_dwordx4 v[206:207], off
	v_lshl_add_u64 v[206:207], s[28:29], 0, v[130:131]
	s_add_i32 m0, s30, 0x2000
	s_nop 0
	global_load_lds_dwordx4 v[206:207], off
	v_lshl_add_u64 v[206:207], v[210:211], 0, s[54:55]
	s_mov_b32 m0, s71
	s_nop 0
	global_load_lds_dwordx4 v[206:207], off
	v_lshl_add_u64 v[206:207], v[212:213], 0, s[54:55]
	s_mov_b32 m0, s72
	s_nop 0
	global_load_lds_dwordx4 v[206:207], off
	s_waitcnt vmcnt(8)
	s_waitcnt lgkmcnt(0)
	s_barrier
	s_setprio 1
	s_waitcnt lgkmcnt(0)
	v_mfma_f32_16x16x32_bf16 v[62:65], v[142:145], v[174:177], v[62:65]
	v_mfma_f32_16x16x32_bf16 v[54:57], v[150:153], v[174:177], v[54:57]
	v_mfma_f32_16x16x32_bf16 v[46:49], v[142:145], v[182:185], v[46:49]
	v_mfma_f32_16x16x32_bf16 v[38:41], v[150:153], v[182:185], v[38:41]
	v_mfma_f32_16x16x32_bf16 v[30:33], v[142:145], v[190:193], v[30:33]
	v_mfma_f32_16x16x32_bf16 v[22:25], v[150:153], v[190:193], v[22:25]
	v_mfma_f32_16x16x32_bf16 v[14:17], v[142:145], v[198:201], v[14:17]
	v_mfma_f32_16x16x32_bf16 v[6:9], v[150:153], v[198:201], v[6:9]
	v_mfma_f32_16x16x32_bf16 v[62:65], v[146:149], v[178:181], v[62:65]
	v_mfma_f32_16x16x32_bf16 v[54:57], v[154:157], v[178:181], v[54:57]
	v_mfma_f32_16x16x32_bf16 v[46:49], v[146:149], v[186:189], v[46:49]
	v_mfma_f32_16x16x32_bf16 v[38:41], v[154:157], v[186:189], v[38:41]
	v_mfma_f32_16x16x32_bf16 v[30:33], v[146:149], v[194:197], v[30:33]
	v_mfma_f32_16x16x32_bf16 v[22:25], v[154:157], v[194:197], v[22:25]
	v_mfma_f32_16x16x32_bf16 v[14:17], v[146:149], v[202:205], v[14:17]
	v_mfma_f32_16x16x32_bf16 v[6:9], v[154:157], v[202:205], v[6:9]
	s_setprio 0
	s_setprio 1
	v_mfma_f32_16x16x32_bf16 v[58:61], v[158:161], v[174:177], v[58:61]
	v_mfma_f32_16x16x32_bf16 v[50:53], v[166:169], v[174:177], v[50:53]
	v_mfma_f32_16x16x32_bf16 v[42:45], v[158:161], v[182:185], v[42:45]
	v_mfma_f32_16x16x32_bf16 v[34:37], v[166:169], v[182:185], v[34:37]
	v_mfma_f32_16x16x32_bf16 v[26:29], v[158:161], v[190:193], v[26:29]
	v_mfma_f32_16x16x32_bf16 v[18:21], v[166:169], v[190:193], v[18:21]
	v_mfma_f32_16x16x32_bf16 v[10:13], v[158:161], v[198:201], v[10:13]
	v_mfma_f32_16x16x32_bf16 v[2:5], v[166:169], v[198:201], v[2:5]
	v_mfma_f32_16x16x32_bf16 v[58:61], v[162:165], v[178:181], v[58:61]
	v_mfma_f32_16x16x32_bf16 v[50:53], v[170:173], v[178:181], v[50:53]
	v_mfma_f32_16x16x32_bf16 v[42:45], v[162:165], v[186:189], v[42:45]
	v_mfma_f32_16x16x32_bf16 v[34:37], v[170:173], v[186:189], v[34:37]
	v_mfma_f32_16x16x32_bf16 v[26:29], v[162:165], v[194:197], v[26:29]
	v_mfma_f32_16x16x32_bf16 v[18:21], v[170:173], v[194:197], v[18:21]
	v_mfma_f32_16x16x32_bf16 v[10:13], v[162:165], v[202:205], v[10:13]
	v_mfma_f32_16x16x32_bf16 v[2:5], v[170:173], v[202:205], v[2:5]
	s_setprio 0
	s_barrier
	s_add_i32 s49, s49, 2
	s_add_u32 s45, s45, 0x100
	s_addc_u32 s48, s48, 0
	s_add_u32 s26, s26, 0x100
	s_addc_u32 s27, s27, 0
	s_cmp_gt_u32 s49, 29
	s_cbranch_scc1 .Lpeel_exit_G3
